# merge: no hand-over barrier between the gate GEMM K loop and the branch GEMM K loop (stage 0 is free by construction)
# baseline (speedup 1.0000x reference)
; DEV int tid_() { int t = threadIdx.x; asm volatile("" : "+v"(t)); return t; }
; template <int NI, bool DEEP = true>
; DEV void gemm_tile(f32x16 (&acc)[2][NI], const bf16* __restrict__ A, int lda, const bf16* __restrict__ Bt, int ldb,
;                    int K, bf16* sA, bf16* sB) {
;   int tid = tid_(), lane = tid & 63, wave = tid >> 6;
;   int wm = wave >> 1, wn = wave & 1;
;   int lr = tid >> 3, lc = (tid & 7) * 8;
;   const bf16* Ap = A + (size_t)lr * lda + lc;
;   const bf16* Bp = Bt + (size_t)lr * ldb + lc;
;   u32x4 ra0[4], rb0[2 * NI], ra1[4], rb1[2 * NI];
; __device__ void phase_merge(PRef p, int l, const bf16* H2, bf16* M, bf16* sA, bf16* sB) {
;     ...
;       f32x16 a1[2][2];
;       zero_acc<2>(a1);
;       gemm_tile<2, false>(a1, U + (size_t)rt * 128 * ldu, ldu, p.WBO + ((size_t)n * 1024 + ct * 128) * 512, 512, 512, sA, sB);
.LBB0_968:
	s_cmp_eq_u32 s95, 2
	s_cselect_b32 s61, s83, 0x200
	s_mul_i32 s0, s15, s61
	s_mul_hi_u32 s1, s14, s61
	s_add_i32 s1, s1, s0
	s_mul_i32 s0, s14, s61
	s_lshl_b64 s[0:1], s[0:1], 1
	s_add_u32 s98, s54, s0
	s_addc_u32 s99, s55, s1
	s_lshl_b64 s[34:35], s[56:57], 10
	s_add_u32 s100, s12, s34
	s_addc_u32 s101, s13, s35
	s_lshl_b32 s56, s61, 1
	s_lshl_b32 s0, s61, 4
	v_and_b32_e32 v0, 63, v196
	v_lshrrev_b32_e32 v1, 6, v196
	v_lshrrev_b32_e32 v2, 3, v0
	v_readfirstlane_b32 s28, v1
	v_lshrrev_b32_e32 v146, 1, v2
	v_and_b32_e32 v147, 7, v0
	v_xor_b32_e32 v146, v147, v146
	v_lshlrev_b32_e32 v146, 4, v146
	v_mul_lo_u32 v134, v2, s56
	v_or_b32_e32 v134, v134, v146
	v_xor_b32_e32 v135, 64, v134
	v_lshl_or_b32 v136, v2, 10, v146
	v_xor_b32_e32 v137, 64, v136
	v_lshrrev_b32_e32 v146, 5, v0
	v_bfe_u32 v147, v0, 1, 3
	v_and_b32_e32 v2, 31, v0
	v_lshrrev_b32_e32 v0, 1, v1
	v_and_b32_e32 v1, 1, v1
	v_lshl_add_u32 v0, v0, 6, v2
	v_lshl_add_u32 v1, v1, 6, v2
	v_lshlrev_b32_e32 v0, 7, v0
	v_lshlrev_b32_e32 v1, 7, v1
	v_add_u32_e32 v1, 0x4000, v1
	v_add_u32_e32 v2, 0, v146
	v_xor_b32_e32 v2, v2, v147
	v_lshl_add_u32 v138, v2, 4, v0
	v_lshl_add_u32 v142, v2, 4, v1
	v_add_u32_e32 v2, 2, v146
	v_xor_b32_e32 v2, v2, v147
	v_lshl_add_u32 v139, v2, 4, v0
	v_lshl_add_u32 v143, v2, 4, v1
	v_add_u32_e32 v2, 4, v146
	v_xor_b32_e32 v2, v2, v147
	v_lshl_add_u32 v140, v2, 4, v0
	v_lshl_add_u32 v144, v2, 4, v1
	v_add_u32_e32 v2, 6, v146
	v_xor_b32_e32 v2, v2, v147
	v_lshl_add_u32 v141, v2, 4, v0
	v_lshl_add_u32 v145, v2, 4, v1
	s_lshl_b32 s1, s56, 5
	s_mul_i32 s1, s1, s28
	s_add_u32 s98, s98, s1
	s_addc_u32 s99, s99, 0
	s_lshl_b32 s1, s28, 15
	s_add_u32 s100, s100, s1
	s_addc_u32 s101, s101, 0
	s_lshl_b32 s28, s28, 12
	s_waitcnt lgkmcnt(0)
	s_add_u32 m0, s28, 0x0
	s_nop 0
	global_load_lds_dwordx4 v134, s[98:99]
	s_add_u32 m0, s28, 0x400
	s_add_u32 s34, s98, s0
	s_addc_u32 s35, s99, 0
	global_load_lds_dwordx4 v135, s[34:35]
	s_add_u32 m0, s28, 0x800
	s_add_u32 s34, s34, s0
	s_addc_u32 s35, s35, 0
	global_load_lds_dwordx4 v134, s[34:35]
	s_add_u32 m0, s28, 0xc00
	s_add_u32 s34, s34, s0
	s_addc_u32 s35, s35, 0
	global_load_lds_dwordx4 v135, s[34:35]
	s_add_u32 m0, s28, 0x4000
	s_nop 0
	global_load_lds_dwordx4 v136, s[100:101]
	s_add_u32 m0, s28, 0x4400
	s_add_u32 s34, s100, 0x2000
	s_addc_u32 s35, s101, 0
	global_load_lds_dwordx4 v137, s[34:35]
	s_add_u32 m0, s28, 0x4800
	s_add_u32 s34, s100, 0x4000
	s_addc_u32 s35, s101, 0
	global_load_lds_dwordx4 v136, s[34:35]
	s_add_u32 m0, s28, 0x4c00
	s_add_u32 s34, s100, 0x6000
	s_addc_u32 s35, s101, 0
	global_load_lds_dwordx4 v137, s[34:35]
	s_add_u32 s98, s98, 0x80
	s_addc_u32 s99, s99, 0
	s_add_u32 s100, s100, 0x80
	s_addc_u32 s101, s101, 0
	v_mov_b32_e32 v20, 0
	v_mov_b32_e32 v21, 0
	v_mov_b32_e32 v22, 0
	v_mov_b32_e32 v23, 0
	v_mov_b32_e32 v24, 0
	v_mov_b32_e32 v25, 0
	v_mov_b32_e32 v26, 0
	v_mov_b32_e32 v27, 0
	v_mov_b32_e32 v28, 0
	v_mov_b32_e32 v29, 0
	v_mov_b32_e32 v30, 0
	v_mov_b32_e32 v31, 0
	v_mov_b32_e32 v32, 0
	v_mov_b32_e32 v33, 0
	v_mov_b32_e32 v34, 0
	v_mov_b32_e32 v35, 0
	v_mov_b32_e32 v36, 0
	v_mov_b32_e32 v37, 0
	v_mov_b32_e32 v38, 0
	v_mov_b32_e32 v39, 0
	v_mov_b32_e32 v40, 0
	v_mov_b32_e32 v41, 0
	v_mov_b32_e32 v42, 0
	v_mov_b32_e32 v43, 0
	v_mov_b32_e32 v44, 0
	v_mov_b32_e32 v45, 0
	v_mov_b32_e32 v46, 0
	v_mov_b32_e32 v47, 0
	v_mov_b32_e32 v48, 0
	v_mov_b32_e32 v49, 0
	v_mov_b32_e32 v50, 0
	v_mov_b32_e32 v51, 0
	v_mov_b32_e32 v52, 0
	v_mov_b32_e32 v53, 0
	v_mov_b32_e32 v54, 0
	v_mov_b32_e32 v55, 0
	v_mov_b32_e32 v56, 0
	v_mov_b32_e32 v57, 0
	v_mov_b32_e32 v58, 0
	v_mov_b32_e32 v59, 0
	v_mov_b32_e32 v60, 0
	v_mov_b32_e32 v61, 0
	v_mov_b32_e32 v62, 0
	v_mov_b32_e32 v63, 0
	v_mov_b32_e32 v64, 0
	v_mov_b32_e32 v65, 0
	v_mov_b32_e32 v66, 0
	v_mov_b32_e32 v67, 0
	v_mov_b32_e32 v84, 0
	v_mov_b32_e32 v85, 0
	v_mov_b32_e32 v86, 0
	v_mov_b32_e32 v87, 0
	v_mov_b32_e32 v88, 0
	v_mov_b32_e32 v89, 0
	v_mov_b32_e32 v90, 0
	v_mov_b32_e32 v91, 0
	v_mov_b32_e32 v92, 0
	v_mov_b32_e32 v93, 0
	v_mov_b32_e32 v94, 0
	v_mov_b32_e32 v95, 0
	v_mov_b32_e32 v96, 0
	v_mov_b32_e32 v97, 0
	v_mov_b32_e32 v98, 0
	v_mov_b32_e32 v99, 0
	s_mov_b32 s57, 0
